# v7 + GEMM main-loop back-edge rotation: pointer bumps and exit test moved ahead of the last barrier
# speedup vs baseline: 1.0062x; 1.0062x over previous
; #define PG8_STAGE(bufoff, gbase, voff) do { _Pragma("unroll") for (int _i = 0; _i < 2; ++_i) \
;         pg8_dma16((const char*)(gbase), (voff)[_i], ldsb + (unsigned)((bufoff) + _i * 8192)); } while (0)
; #define PG8_LDA(dst, b, h) do { _Pragma("unroll") for (int m = 0; m < 4; ++m) _Pragma("unroll") for (int k = 0; k < 2; ++k) dst[m][k] = *(const PG8_LAS bf16x8*)(lds + PG8_SA(b, h) + aoff + m * 2048 + k * 1024); } while (0)
; #define PG8_LDB(dst, b, h) do { _Pragma("unroll") for (int n = 0; n < 2; ++n) _Pragma("unroll") for (int k = 0; k < 2; ++k) dst[n][k] = *(const PG8_LAS bf16x8*)(lds + PG8_SB(b, h) + boff + n * 2048 + k * 1024); } while (0)
; #define PG8_MMA(ai, bj, At, Bt) do { __builtin_amdgcn_s_setprio(1); _Pragma("unroll") for (int m = 0; m < 4; ++m) _Pragma("unroll") for (int n = 0; n < 2; ++n) _Pragma("unroll") for (int k = 0; k < 2; ++k) \
;         acc[ai][bj][m][n] = __builtin_amdgcn_mfma_f32_16x16x32_bf16(Bt[n][k], At[m][k], acc[ai][bj][m][n], 0, 0, 0); __builtin_amdgcn_s_setprio(0); } while (0)
; #define PG8_WAIT_V(n) asm volatile("s_waitcnt vmcnt(" #n ")" ::: "memory")
; #define PG8_WAIT_L(n) asm volatile("s_waitcnt lgkmcnt(" #n ")" ::: "memory")
; #define PG8_BAR __builtin_amdgcn_s_barrier()
; #define PG8_SCHED __builtin_amdgcn_sched_barrier(0)
; template <class Epi, class Sched, bool ALIGN_EPI = false, bool SP2 = false>
; __device__ __forceinline__ void gemm_phase(PG8_LAS unsigned char* lds, const Gemm g, const Sched& S, const Epi& E) {
;     ...
;             const bool last = (t == nt - 2);
;             const char* a1 = cA + (size_t)(t + 1) * kstep;
;             const char* a2 = last ? nA : cA + (size_t)(t + 2) * kstep; const char* b2 = last ? nB : cB + (size_t)(t + 2) * kstep;
;             const char* a3 = a2 + kstep; const char* b3 = b2 + kstep;
;             if (last && has_next) S.a_ready(nxt);
;             if constexpr (SP2) {
;             PG8_LDB(B0, 0, 0); PG8_LDB(B1, 0, 1); PG8_SCHED; PG8_LDA(At, 0, 0); PG8_STAGE(PG8_SA(1, 1), a1 + hstep, voffA);
;             PG8_WAIT_V(8); PG8_WAIT_L(0); PG8_BAR; PG8_MMA(0, 0, At, B0); PG8_MMA(0, 1, At, B1); PG8_BAR; PG8_SCHED;
;             PG8_LDA(At, 0, 1); PG8_STAGE(PG8_SB(0, 0), b2, voffB); PG8_STAGE(PG8_SB(0, 1), b2 + hstep, voffB); PG8_STAGE(PG8_SA(0, 0), a2, voffA);
;             PG8_WAIT_V(8); PG8_WAIT_L(0); PG8_BAR; PG8_MMA(1, 0, At, B0); PG8_MMA(1, 1, At, B1); PG8_BAR; PG8_SCHED;
.LBB0_305:
	v_add_u32_e32 v140, 0x10000, v207
	v_add_u32_e32 v160, 0x14000, v207
	ds_read_b128 v[128:131], v140
	ds_read_b128 v[132:135], v140 offset:1024
	ds_read_b128 v[136:139], v140 offset:2048
	ds_read_b128 v[140:143], v140 offset:3072
	ds_read_b128 v[144:147], v160
	ds_read_b128 v[152:155], v160 offset:1024
	ds_read_b128 v[156:159], v160 offset:2048
	ds_read_b128 v[160:163], v160 offset:3072
	s_add_i32 s58, s12, 2
	s_cmp_eq_u32 s77, s12
	s_cselect_b32 s40, s30, s72
	s_cselect_b32 s41, s31, s95
	s_cselect_b32 s36, s34, vcc_lo
	s_cselect_b32 s37, s35, vcc_hi
	s_add_u32 s12, s40, 0x80
	s_addc_u32 s13, s41, 0
	ds_read_b128 v[164:167], v208
	ds_read_b128 v[168:171], v208 offset:1024
	ds_read_b128 v[172:175], v208 offset:2048
	ds_read_b128 v[176:179], v208 offset:3072
	ds_read_b128 v[180:183], v208 offset:4096
	ds_read_b128 v[210:213], v208 offset:5120
	ds_read_b128 v[214:217], v208 offset:6144
	ds_read_b128 v[218:221], v208 offset:7168
	s_mov_b32 s4, m0
	s_mov_b32 m0, s78
	s_nop 0
	global_load_lds_dwordx4 v148, s[10:11]
	s_mov_b32 m0, s4
	s_nop 0
	s_mov_b32 s4, m0
	s_mov_b32 m0, s80
	s_nop 0
	global_load_lds_dwordx4 v198, s[10:11]
	s_mov_b32 m0, s4
	s_waitcnt vmcnt(8)
	s_waitcnt lgkmcnt(0)
	s_barrier
	s_setprio 1
	s_waitcnt lgkmcnt(7)
	v_mfma_f32_16x16x32_bf16 v[124:127], v[128:131], v[164:167], v[124:127]
	v_mfma_f32_16x16x32_bf16 v[116:119], v[136:139], v[164:167], v[116:119]
	s_waitcnt lgkmcnt(5)
	v_mfma_f32_16x16x32_bf16 v[108:111], v[128:131], v[172:175], v[108:111]
	v_mfma_f32_16x16x32_bf16 v[100:103], v[136:139], v[172:175], v[100:103]
	s_waitcnt lgkmcnt(3)
	v_mfma_f32_16x16x32_bf16 v[92:95], v[128:131], v[180:183], v[92:95]
	v_mfma_f32_16x16x32_bf16 v[84:87], v[136:139], v[180:183], v[84:87]
	s_waitcnt lgkmcnt(1)
	v_mfma_f32_16x16x32_bf16 v[76:79], v[128:131], v[214:217], v[76:79]
	v_mfma_f32_16x16x32_bf16 v[68:71], v[136:139], v[214:217], v[68:71]
	v_mfma_f32_16x16x32_bf16 v[124:127], v[132:135], v[168:171], v[124:127]
	v_mfma_f32_16x16x32_bf16 v[116:119], v[140:143], v[168:171], v[116:119]
	v_mfma_f32_16x16x32_bf16 v[108:111], v[132:135], v[176:179], v[108:111]
	v_mfma_f32_16x16x32_bf16 v[100:103], v[140:143], v[176:179], v[100:103]
	v_mfma_f32_16x16x32_bf16 v[92:95], v[132:135], v[210:213], v[92:95]
	v_mfma_f32_16x16x32_bf16 v[84:87], v[140:143], v[210:213], v[84:87]
	s_waitcnt lgkmcnt(0)
	v_mfma_f32_16x16x32_bf16 v[76:79], v[132:135], v[218:221], v[76:79]
	v_mfma_f32_16x16x32_bf16 v[68:71], v[140:143], v[218:221], v[68:71]
	s_setprio 0
	s_setprio 1
	v_mfma_f32_16x16x32_bf16 v[120:123], v[144:147], v[164:167], v[120:123]
	v_mfma_f32_16x16x32_bf16 v[112:115], v[156:159], v[164:167], v[112:115]
	v_mfma_f32_16x16x32_bf16 v[104:107], v[144:147], v[172:175], v[104:107]
	v_mfma_f32_16x16x32_bf16 v[96:99], v[156:159], v[172:175], v[96:99]
	v_mfma_f32_16x16x32_bf16 v[88:91], v[144:147], v[180:183], v[88:91]
	v_mfma_f32_16x16x32_bf16 v[80:83], v[156:159], v[180:183], v[80:83]
	v_mfma_f32_16x16x32_bf16 v[72:75], v[144:147], v[214:217], v[72:75]
	v_mfma_f32_16x16x32_bf16 v[64:67], v[156:159], v[214:217], v[64:67]
	v_mfma_f32_16x16x32_bf16 v[120:123], v[152:155], v[168:171], v[120:123]
	v_mfma_f32_16x16x32_bf16 v[112:115], v[160:163], v[168:171], v[112:115]
	v_mfma_f32_16x16x32_bf16 v[104:107], v[152:155], v[176:179], v[104:107]
	v_mfma_f32_16x16x32_bf16 v[96:99], v[160:163], v[176:179], v[96:99]
	v_mfma_f32_16x16x32_bf16 v[88:91], v[152:155], v[210:213], v[88:91]
	v_mfma_f32_16x16x32_bf16 v[80:83], v[160:163], v[210:213], v[80:83]
	v_mfma_f32_16x16x32_bf16 v[72:75], v[152:155], v[218:221], v[72:75]
	v_mfma_f32_16x16x32_bf16 v[64:67], v[160:163], v[218:221], v[64:67]
	s_setprio 0
	s_barrier
	ds_read_b128 v[164:167], v208 offset:16384
	ds_read_b128 v[168:171], v208 offset:17408
	ds_read_b128 v[172:175], v208 offset:18432
	ds_read_b128 v[176:179], v208 offset:19456
	ds_read_b128 v[180:183], v208 offset:20480
	ds_read_b128 v[210:213], v208 offset:21504
	ds_read_b128 v[214:217], v208 offset:22528
	ds_read_b128 v[218:221], v208 offset:23552
	s_mov_b32 s4, m0
	s_mov_b32 m0, s50
	s_nop 0
	global_load_lds_dwordx4 v151, s[36:37]
	s_mov_b32 m0, s4
	s_nop 0
	s_mov_b32 s4, m0
	s_mov_b32 m0, s51
	s_nop 0
	global_load_lds_dwordx4 v199, s[36:37]
	s_mov_b32 m0, s4
	s_add_u32 s4, s36, s47
	s_addc_u32 s5, s37, 0
	s_mov_b32 s6, m0
	s_mov_b32 m0, s61
	s_nop 0
	global_load_lds_dwordx4 v151, s[4:5]
	s_mov_b32 m0, s6
	s_nop 0
	s_mov_b32 s6, m0
	s_mov_b32 m0, s62
	s_nop 0
	global_load_lds_dwordx4 v199, s[4:5]
	s_mov_b32 m0, s6
	s_mov_b32 s4, m0
	s_mov_b32 m0, s49
	s_nop 0
	global_load_lds_dwordx4 v148, s[40:41]
	s_mov_b32 m0, s4
	s_nop 0
	s_mov_b32 s4, m0
	s_mov_b32 m0, s63
	s_nop 0
	global_load_lds_dwordx4 v198, s[40:41]
	s_mov_b32 m0, s4
	s_waitcnt vmcnt(8)
	s_waitcnt lgkmcnt(0)
	s_barrier
; #define PG8_STAGE(bufoff, gbase, voff) do { _Pragma("unroll") for (int _i = 0; _i < 2; ++_i) \
;         pg8_dma16((const char*)(gbase), (voff)[_i], ldsb + (unsigned)((bufoff) + _i * 8192)); } while (0)
; #define PG8_LDA(dst, b, h) do { _Pragma("unroll") for (int m = 0; m < 4; ++m) _Pragma("unroll") for (int k = 0; k < 2; ++k) dst[m][k] = *(const PG8_LAS bf16x8*)(lds + PG8_SA(b, h) + aoff + m * 2048 + k * 1024); } while (0)
; #define PG8_LDB(dst, b, h) do { _Pragma("unroll") for (int n = 0; n < 2; ++n) _Pragma("unroll") for (int k = 0; k < 2; ++k) dst[n][k] = *(const PG8_LAS bf16x8*)(lds + PG8_SB(b, h) + boff + n * 2048 + k * 1024); } while (0)
; #define PG8_MMA(ai, bj, At, Bt) do { __builtin_amdgcn_s_setprio(1); _Pragma("unroll") for (int m = 0; m < 4; ++m) _Pragma("unroll") for (int n = 0; n < 2; ++n) _Pragma("unroll") for (int k = 0; k < 2; ++k) \
;         acc[ai][bj][m][n] = __builtin_amdgcn_mfma_f32_16x16x32_bf16(Bt[n][k], At[m][k], acc[ai][bj][m][n], 0, 0, 0); __builtin_amdgcn_s_setprio(0); } while (0)
; #define PG8_WAIT_V(n) asm volatile("s_waitcnt vmcnt(" #n ")" ::: "memory")
; #define PG8_WAIT_L(n) asm volatile("s_waitcnt lgkmcnt(" #n ")" ::: "memory")
; #define PG8_BAR __builtin_amdgcn_s_barrier()
; #define PG8_SCHED __builtin_amdgcn_sched_barrier(0)
; template <class Epi, class Sched, bool ALIGN_EPI = false, bool SP2 = false>
; __device__ __forceinline__ void gemm_phase(PG8_LAS unsigned char* lds, const Gemm g, const Sched& S, const Epi& E) {
;     ...
;             PG8_WAIT_V(8); PG8_WAIT_L(0); PG8_BAR; PG8_MMA(1, 0, At, B0); PG8_MMA(1, 1, At, B1); PG8_BAR; PG8_SCHED;
;             PG8_LDB(B0, 1, 0); PG8_LDB(B1, 1, 1); PG8_SCHED; PG8_LDA(At, 1, 0); PG8_STAGE(PG8_SA(0, 1), a2 + hstep, voffA);
;             PG8_WAIT_V(8); PG8_WAIT_L(0); PG8_BAR; PG8_MMA(0, 0, At, B0); PG8_MMA(0, 1, At, B1); PG8_BAR; PG8_SCHED;
	s_setprio 1
	s_waitcnt lgkmcnt(7)
	v_mfma_f32_16x16x32_bf16 v[60:63], v[128:131], v[164:167], v[60:63]
	v_mfma_f32_16x16x32_bf16 v[52:55], v[136:139], v[164:167], v[52:55]
	s_waitcnt lgkmcnt(5)
	v_mfma_f32_16x16x32_bf16 v[44:47], v[128:131], v[172:175], v[44:47]
	v_mfma_f32_16x16x32_bf16 v[36:39], v[136:139], v[172:175], v[36:39]
	s_waitcnt lgkmcnt(3)
	v_mfma_f32_16x16x32_bf16 v[28:31], v[128:131], v[180:183], v[28:31]
	v_mfma_f32_16x16x32_bf16 v[20:23], v[136:139], v[180:183], v[20:23]
	s_waitcnt lgkmcnt(1)
	v_mfma_f32_16x16x32_bf16 v[12:15], v[128:131], v[214:217], v[12:15]
	v_mfma_f32_16x16x32_bf16 v[4:7], v[136:139], v[214:217], v[4:7]
	v_mfma_f32_16x16x32_bf16 v[60:63], v[132:135], v[168:171], v[60:63]
	v_mfma_f32_16x16x32_bf16 v[52:55], v[140:143], v[168:171], v[52:55]
	v_mfma_f32_16x16x32_bf16 v[44:47], v[132:135], v[176:179], v[44:47]
	v_mfma_f32_16x16x32_bf16 v[36:39], v[140:143], v[176:179], v[36:39]
	v_mfma_f32_16x16x32_bf16 v[28:31], v[132:135], v[210:213], v[28:31]
	v_mfma_f32_16x16x32_bf16 v[20:23], v[140:143], v[210:213], v[20:23]
	s_waitcnt lgkmcnt(0)
	v_mfma_f32_16x16x32_bf16 v[12:15], v[132:135], v[218:221], v[12:15]
	v_mfma_f32_16x16x32_bf16 v[4:7], v[140:143], v[218:221], v[4:7]
	s_setprio 0
	s_setprio 1
	v_mfma_f32_16x16x32_bf16 v[56:59], v[144:147], v[164:167], v[56:59]
	v_mfma_f32_16x16x32_bf16 v[48:51], v[156:159], v[164:167], v[48:51]
	v_mfma_f32_16x16x32_bf16 v[40:43], v[144:147], v[172:175], v[40:43]
	v_mfma_f32_16x16x32_bf16 v[32:35], v[156:159], v[172:175], v[32:35]
	v_mfma_f32_16x16x32_bf16 v[24:27], v[144:147], v[180:183], v[24:27]
	v_mfma_f32_16x16x32_bf16 v[16:19], v[156:159], v[180:183], v[16:19]
	v_mfma_f32_16x16x32_bf16 v[8:11], v[144:147], v[214:217], v[8:11]
	v_mfma_f32_16x16x32_bf16 v[0:3], v[156:159], v[214:217], v[0:3]
	v_mfma_f32_16x16x32_bf16 v[56:59], v[152:155], v[168:171], v[56:59]
	v_mfma_f32_16x16x32_bf16 v[48:51], v[160:163], v[168:171], v[48:51]
	v_mfma_f32_16x16x32_bf16 v[40:43], v[152:155], v[176:179], v[40:43]
	v_mfma_f32_16x16x32_bf16 v[32:35], v[160:163], v[176:179], v[32:35]
	v_mfma_f32_16x16x32_bf16 v[24:27], v[152:155], v[210:213], v[24:27]
	v_mfma_f32_16x16x32_bf16 v[16:19], v[160:163], v[210:213], v[16:19]
	v_mfma_f32_16x16x32_bf16 v[8:11], v[152:155], v[218:221], v[8:11]
	v_mfma_f32_16x16x32_bf16 v[0:3], v[160:163], v[218:221], v[0:3]
	s_setprio 0
	s_barrier
	v_add_u32_e32 v140, 0x18000, v207
	v_add_u32_e32 v160, 0x1c000, v207
	ds_read_b128 v[128:131], v140
	ds_read_b128 v[132:135], v140 offset:1024
	ds_read_b128 v[136:139], v140 offset:2048
	ds_read_b128 v[140:143], v140 offset:3072
	ds_read_b128 v[144:147], v160
	ds_read_b128 v[152:155], v160 offset:1024
	ds_read_b128 v[156:159], v160 offset:2048
	ds_read_b128 v[160:163], v160 offset:3072
	ds_read_b128 v[164:167], v208 offset:32768
	ds_read_b128 v[168:171], v208 offset:33792
	ds_read_b128 v[172:175], v208 offset:34816
	ds_read_b128 v[176:179], v208 offset:35840
	ds_read_b128 v[180:183], v208 offset:36864
	ds_read_b128 v[210:213], v208 offset:37888
	ds_read_b128 v[214:217], v208 offset:38912
	ds_read_b128 v[218:221], v208 offset:39936
	s_add_u32 s4, s40, s47
	s_addc_u32 s5, s41, 0
	s_mov_b32 s6, m0
	s_mov_b32 m0, s64
	s_nop 0
	global_load_lds_dwordx4 v148, s[4:5]
	s_mov_b32 m0, s6
	s_nop 0
	s_mov_b32 s6, m0
	s_mov_b32 m0, s65
	s_nop 0
	global_load_lds_dwordx4 v198, s[4:5]
	s_mov_b32 m0, s6
	s_waitcnt vmcnt(8)
	s_waitcnt lgkmcnt(0)
	s_barrier
	s_setprio 1
	s_waitcnt lgkmcnt(7)
	v_mfma_f32_16x16x32_bf16 v[124:127], v[128:131], v[164:167], v[124:127]
	v_mfma_f32_16x16x32_bf16 v[116:119], v[136:139], v[164:167], v[116:119]
	s_waitcnt lgkmcnt(5)
	v_mfma_f32_16x16x32_bf16 v[108:111], v[128:131], v[172:175], v[108:111]
	v_mfma_f32_16x16x32_bf16 v[100:103], v[136:139], v[172:175], v[100:103]
	s_waitcnt lgkmcnt(3)
	v_mfma_f32_16x16x32_bf16 v[92:95], v[128:131], v[180:183], v[92:95]
	v_mfma_f32_16x16x32_bf16 v[84:87], v[136:139], v[180:183], v[84:87]
	s_waitcnt lgkmcnt(1)
	v_mfma_f32_16x16x32_bf16 v[76:79], v[128:131], v[214:217], v[76:79]
	v_mfma_f32_16x16x32_bf16 v[68:71], v[136:139], v[214:217], v[68:71]
	v_mfma_f32_16x16x32_bf16 v[124:127], v[132:135], v[168:171], v[124:127]
	v_mfma_f32_16x16x32_bf16 v[116:119], v[140:143], v[168:171], v[116:119]
	v_mfma_f32_16x16x32_bf16 v[108:111], v[132:135], v[176:179], v[108:111]
	v_mfma_f32_16x16x32_bf16 v[100:103], v[140:143], v[176:179], v[100:103]
	v_mfma_f32_16x16x32_bf16 v[92:95], v[132:135], v[210:213], v[92:95]
	v_mfma_f32_16x16x32_bf16 v[84:87], v[140:143], v[210:213], v[84:87]
	s_waitcnt lgkmcnt(0)
	v_mfma_f32_16x16x32_bf16 v[76:79], v[132:135], v[218:221], v[76:79]
	v_mfma_f32_16x16x32_bf16 v[68:71], v[140:143], v[218:221], v[68:71]
	s_setprio 0
	s_setprio 1
	v_mfma_f32_16x16x32_bf16 v[120:123], v[144:147], v[164:167], v[120:123]
	v_mfma_f32_16x16x32_bf16 v[112:115], v[156:159], v[164:167], v[112:115]
	v_mfma_f32_16x16x32_bf16 v[104:107], v[144:147], v[172:175], v[104:107]
	v_mfma_f32_16x16x32_bf16 v[96:99], v[156:159], v[172:175], v[96:99]
	v_mfma_f32_16x16x32_bf16 v[88:91], v[144:147], v[180:183], v[88:91]
	v_mfma_f32_16x16x32_bf16 v[80:83], v[156:159], v[180:183], v[80:83]
	v_mfma_f32_16x16x32_bf16 v[72:75], v[144:147], v[214:217], v[72:75]
	v_mfma_f32_16x16x32_bf16 v[64:67], v[156:159], v[214:217], v[64:67]
	v_mfma_f32_16x16x32_bf16 v[120:123], v[152:155], v[168:171], v[120:123]
	v_mfma_f32_16x16x32_bf16 v[112:115], v[160:163], v[168:171], v[112:115]
	v_mfma_f32_16x16x32_bf16 v[104:107], v[152:155], v[176:179], v[104:107]
	v_mfma_f32_16x16x32_bf16 v[96:99], v[160:163], v[176:179], v[96:99]
	v_mfma_f32_16x16x32_bf16 v[88:91], v[152:155], v[210:213], v[88:91]
	v_mfma_f32_16x16x32_bf16 v[80:83], v[160:163], v[210:213], v[80:83]
	v_mfma_f32_16x16x32_bf16 v[72:75], v[152:155], v[218:221], v[72:75]
	v_mfma_f32_16x16x32_bf16 v[64:67], v[160:163], v[218:221], v[64:67]
	s_setprio 0
	s_barrier
; #define PG8_STAGE(bufoff, gbase, voff) do { _Pragma("unroll") for (int _i = 0; _i < 2; ++_i) \
;         pg8_dma16((const char*)(gbase), (voff)[_i], ldsb + (unsigned)((bufoff) + _i * 8192)); } while (0)
; #define PG8_LDA(dst, b, h) do { _Pragma("unroll") for (int m = 0; m < 4; ++m) _Pragma("unroll") for (int k = 0; k < 2; ++k) dst[m][k] = *(const PG8_LAS bf16x8*)(lds + PG8_SA(b, h) + aoff + m * 2048 + k * 1024); } while (0)
; #define PG8_MMA(ai, bj, At, Bt) do { __builtin_amdgcn_s_setprio(1); _Pragma("unroll") for (int m = 0; m < 4; ++m) _Pragma("unroll") for (int n = 0; n < 2; ++n) _Pragma("unroll") for (int k = 0; k < 2; ++k) \
;         acc[ai][bj][m][n] = __builtin_amdgcn_mfma_f32_16x16x32_bf16(Bt[n][k], At[m][k], acc[ai][bj][m][n], 0, 0, 0); __builtin_amdgcn_s_setprio(0); } while (0)
; #define PG8_WAIT_V(n) asm volatile("s_waitcnt vmcnt(" #n ")" ::: "memory")
; #define PG8_WAIT_L(n) asm volatile("s_waitcnt lgkmcnt(" #n ")" ::: "memory")
; #define PG8_BAR __builtin_amdgcn_s_barrier()
; #define PG8_SCHED __builtin_amdgcn_sched_barrier(0)
; template <class Epi, class Sched, bool ALIGN_EPI = false, bool SP2 = false>
; __device__ __forceinline__ void gemm_phase(PG8_LAS unsigned char* lds, const Gemm g, const Sched& S, const Epi& E) {
;     ...
;             PG8_LDA(At, 1, 1); PG8_STAGE(PG8_SB(1, 0), b3, voffB); PG8_STAGE(PG8_SB(1, 1), b3 + hstep, voffB); PG8_STAGE(PG8_SA(1, 0), a3, voffA);
;             PG8_WAIT_V(8); PG8_WAIT_L(0); PG8_BAR; PG8_MMA(1, 0, At, B0); PG8_MMA(1, 1, At, B1); PG8_BAR; PG8_SCHED;
;     ...
;         if constexpr (ALIGN_EPI) { if (wr == 0) PG8_BAR; }
	ds_read_b128 v[164:167], v208 offset:49152
	ds_read_b128 v[168:171], v208 offset:50176
	ds_read_b128 v[172:175], v208 offset:51200
	ds_read_b128 v[176:179], v208 offset:52224
	ds_read_b128 v[180:183], v208 offset:53248
	ds_read_b128 v[210:213], v208 offset:54272
	ds_read_b128 v[214:217], v208 offset:55296
	ds_read_b128 v[218:221], v208 offset:56320
	s_add_u32 s4, s36, 0x80
	s_addc_u32 s5, s37, 0
	s_mov_b32 s6, m0
	s_mov_b32 m0, s67
	s_nop 0
	global_load_lds_dwordx4 v151, s[4:5]
	s_mov_b32 m0, s6
	s_nop 0
	s_mov_b32 s6, m0
	s_mov_b32 m0, s70
	s_nop 0
	global_load_lds_dwordx4 v199, s[4:5]
	s_mov_b32 m0, s6
	s_add_u32 s4, s4, s47
	s_addc_u32 s5, s5, 0
	s_mov_b32 s6, m0
	s_mov_b32 m0, s75
	s_nop 0
	global_load_lds_dwordx4 v151, s[4:5]
	s_mov_b32 m0, s6
	s_nop 0
	s_mov_b32 s6, m0
	s_mov_b32 m0, s76
	s_nop 0
	global_load_lds_dwordx4 v199, s[4:5]
	s_mov_b32 m0, s6
	s_mov_b32 s4, m0
	s_mov_b32 m0, s71
	s_nop 0
	global_load_lds_dwordx4 v148, s[12:13]
	s_mov_b32 m0, s4
	s_nop 0
	s_mov_b32 s4, m0
	s_mov_b32 m0, s74
	s_nop 0
	global_load_lds_dwordx4 v198, s[12:13]
	s_mov_b32 m0, s4
	s_add_u32 s72, s72, 0x100
	s_addc_u32 s95, s95, 0
	s_add_u32 vcc_lo, vcc_lo, 0x100
	s_addc_u32 vcc_hi, vcc_hi, 0
	s_add_u32 s10, s10, 0x100
	s_addc_u32 s11, s11, 0
	s_mov_b32 s12, s58
	s_cmp_ge_u32 s58, s60
	s_waitcnt vmcnt(8)
	s_waitcnt lgkmcnt(0)
	s_barrier
	s_setprio 1
	s_waitcnt lgkmcnt(7)
	v_mfma_f32_16x16x32_bf16 v[60:63], v[128:131], v[164:167], v[60:63]
	v_mfma_f32_16x16x32_bf16 v[52:55], v[136:139], v[164:167], v[52:55]
	s_waitcnt lgkmcnt(5)
	v_mfma_f32_16x16x32_bf16 v[44:47], v[128:131], v[172:175], v[44:47]
	v_mfma_f32_16x16x32_bf16 v[36:39], v[136:139], v[172:175], v[36:39]
	s_waitcnt lgkmcnt(3)
	v_mfma_f32_16x16x32_bf16 v[28:31], v[128:131], v[180:183], v[28:31]
	v_mfma_f32_16x16x32_bf16 v[20:23], v[136:139], v[180:183], v[20:23]
	s_waitcnt lgkmcnt(1)
	v_mfma_f32_16x16x32_bf16 v[12:15], v[128:131], v[214:217], v[12:15]
	v_mfma_f32_16x16x32_bf16 v[4:7], v[136:139], v[214:217], v[4:7]
	v_mfma_f32_16x16x32_bf16 v[60:63], v[132:135], v[168:171], v[60:63]
	v_mfma_f32_16x16x32_bf16 v[52:55], v[140:143], v[168:171], v[52:55]
	v_mfma_f32_16x16x32_bf16 v[44:47], v[132:135], v[176:179], v[44:47]
	v_mfma_f32_16x16x32_bf16 v[36:39], v[140:143], v[176:179], v[36:39]
	v_mfma_f32_16x16x32_bf16 v[28:31], v[132:135], v[210:213], v[28:31]
	v_mfma_f32_16x16x32_bf16 v[20:23], v[140:143], v[210:213], v[20:23]
	s_waitcnt lgkmcnt(0)
	v_mfma_f32_16x16x32_bf16 v[12:15], v[132:135], v[218:221], v[12:15]
	v_mfma_f32_16x16x32_bf16 v[4:7], v[140:143], v[218:221], v[4:7]
	s_setprio 0
	s_setprio 1
	v_mfma_f32_16x16x32_bf16 v[56:59], v[144:147], v[164:167], v[56:59]
	v_mfma_f32_16x16x32_bf16 v[48:51], v[156:159], v[164:167], v[48:51]
	v_mfma_f32_16x16x32_bf16 v[40:43], v[144:147], v[172:175], v[40:43]
	v_mfma_f32_16x16x32_bf16 v[32:35], v[156:159], v[172:175], v[32:35]
	v_mfma_f32_16x16x32_bf16 v[24:27], v[144:147], v[180:183], v[24:27]
	v_mfma_f32_16x16x32_bf16 v[16:19], v[156:159], v[180:183], v[16:19]
	v_mfma_f32_16x16x32_bf16 v[8:11], v[144:147], v[214:217], v[8:11]
	v_mfma_f32_16x16x32_bf16 v[0:3], v[156:159], v[214:217], v[0:3]
	v_mfma_f32_16x16x32_bf16 v[56:59], v[152:155], v[168:171], v[56:59]
	v_mfma_f32_16x16x32_bf16 v[48:51], v[160:163], v[168:171], v[48:51]
	v_mfma_f32_16x16x32_bf16 v[40:43], v[152:155], v[176:179], v[40:43]
	v_mfma_f32_16x16x32_bf16 v[32:35], v[160:163], v[176:179], v[32:35]
	v_mfma_f32_16x16x32_bf16 v[24:27], v[152:155], v[210:213], v[24:27]
	v_mfma_f32_16x16x32_bf16 v[16:19], v[160:163], v[210:213], v[16:19]
	v_mfma_f32_16x16x32_bf16 v[8:11], v[152:155], v[218:221], v[8:11]
	v_mfma_f32_16x16x32_bf16 v[0:3], v[160:163], v[218:221], v[0:3]
	s_setprio 0
	s_barrier
	s_cbranch_scc0 .LBB0_305
	s_and_b64 vcc, exec, s[24:25]
	s_cbranch_vccz .LBB0_309
	s_barrier
	s_lshl_b32 s40, s94, 8
	s_cmp_lt_i32 s93, 2
	s_mov_b64 s[10:11], -1
	s_cbranch_scc0 .LBB0_310
